# adds: P5 scan loads issued at phase start and decay table preloaded with ds_read_b128
# speedup vs baseline: 1.0158x; 1.0072x over previous
; __device__ __forceinline__ unsigned cvt_pk_bf16(float lo, float hi) { unsigned r; asm volatile("v_cvt_pk_bf16_f32 %0, %1, %2" : "=v"(r) : "v"(lo), "v"(hi)); return r; }
; __device__ __forceinline__ void mlstm_state_scan(const Frame& F) {
;     ...
;     if (F.tid < 128) { const int h = F.tid >> 5, c = F.tid & 31; const float* MR = MRb + h * SP; sdec[F.tid] = expf((c == 0 ? 0.f : MR[c * LC - 1]) - MR[c * LC + LC - 1]); }
;     __syncthreads();
;     const int gt = F.bid * 512 + F.tid, GT = F.G * 512;
;     typedef float f32x2 __attribute__((ext_vector_type(2)));
;     for (int e2 = gt; e2 < 131072; e2 += GT) { const int h = e2 >> 15;
;         f32x2 C = (f32x2){0.f, 0.f};
; #pragma unroll 1
;         for (int c0 = 0; c0 < NCH; c0 += 8) { f32x2 u[8];
; #pragma unroll
;             for (int k = 0; k < 8; ++k) u[k] = *(const f32x2*)(U + (size_t)(c0 + k) * 262144 + (size_t)e2 * 2);
; #pragma unroll
;             for (int k = 0; k < 8; ++k) { *(unsigned*)(CST + (size_t)(c0 + k) * 262144 + (size_t)e2 * 2) = cvt_pk_bf16(C[0], C[1]); C = C * sdec[h * 32 + c0 + k] + u[k]; } }
.LBB0_672:
	s_cmp_lt_i32 s86, 6
	s_cselect_b64 s[2:3], -1, 0
	s_waitcnt lgkmcnt(0)
	s_and_b64 s[18:19], s[2:3], s[0:1]
	s_andn2_b64 vcc, exec, s[18:19]
	s_cbranch_vccnz .LBB0_686
	v_lshl_add_u32 v104, s33, 9, v144
	v_lshlrev_b32_e32 v104, 3, v104
	v_mov_b32_e32 v105, 0
	v_lshl_add_u64 v[12:13], s[84:85], 0, v[104:105]
	v_add_co_u32_e32 v14, vcc, 0x17dc0000, v12
	s_nop 1
	v_addc_co_u32_e32 v15, vcc, 0, v13, vcc
	global_load_dwordx2 v[40:41], v[14:15], off offset:256
	v_add_co_u32_e32 v14, vcc, 0x17ec0000, v12
	s_nop 1
	v_addc_co_u32_e32 v15, vcc, 0, v13, vcc
	global_load_dwordx2 v[42:43], v[14:15], off offset:256
	v_add_co_u32_e32 v14, vcc, 0x17fc0000, v12
	s_nop 1
	v_addc_co_u32_e32 v15, vcc, 0, v13, vcc
	global_load_dwordx2 v[44:45], v[14:15], off offset:256
	v_add_co_u32_e32 v14, vcc, 0x180c0000, v12
	s_nop 1
	v_addc_co_u32_e32 v15, vcc, 0, v13, vcc
	global_load_dwordx2 v[46:47], v[14:15], off offset:256
	v_add_co_u32_e32 v14, vcc, 0x181c0000, v12
	s_nop 1
	v_addc_co_u32_e32 v15, vcc, 0, v13, vcc
	global_load_dwordx2 v[48:49], v[14:15], off offset:256
	v_add_co_u32_e32 v14, vcc, 0x182c0000, v12
	s_nop 1
	v_addc_co_u32_e32 v15, vcc, 0, v13, vcc
	global_load_dwordx2 v[50:51], v[14:15], off offset:256
	v_add_co_u32_e32 v14, vcc, 0x183c0000, v12
	s_nop 1
	v_addc_co_u32_e32 v15, vcc, 0, v13, vcc
	global_load_dwordx2 v[52:53], v[14:15], off offset:256
	v_add_co_u32_e32 v14, vcc, 0x184c0000, v12
	s_nop 1
	v_addc_co_u32_e32 v15, vcc, 0, v13, vcc
	global_load_dwordx2 v[54:55], v[14:15], off offset:256
	v_add_co_u32_e32 v14, vcc, 0x185c0000, v12
	s_nop 1
	v_addc_co_u32_e32 v15, vcc, 0, v13, vcc
	global_load_dwordx2 v[56:57], v[14:15], off offset:256
	v_add_co_u32_e32 v14, vcc, 0x186c0000, v12
	s_nop 1
	v_addc_co_u32_e32 v15, vcc, 0, v13, vcc
	global_load_dwordx2 v[58:59], v[14:15], off offset:256
	v_add_co_u32_e32 v14, vcc, 0x187c0000, v12
	s_nop 1
	v_addc_co_u32_e32 v15, vcc, 0, v13, vcc
	global_load_dwordx2 v[60:61], v[14:15], off offset:256
	v_add_co_u32_e32 v14, vcc, 0x188c0000, v12
	s_nop 1
	v_addc_co_u32_e32 v15, vcc, 0, v13, vcc
	global_load_dwordx2 v[62:63], v[14:15], off offset:256
	v_add_co_u32_e32 v14, vcc, 0x189c0000, v12
	s_nop 1
	v_addc_co_u32_e32 v15, vcc, 0, v13, vcc
	global_load_dwordx2 v[64:65], v[14:15], off offset:256
	v_add_co_u32_e32 v14, vcc, 0x18ac0000, v12
	s_nop 1
	v_addc_co_u32_e32 v15, vcc, 0, v13, vcc
	global_load_dwordx2 v[66:67], v[14:15], off offset:256
	v_add_co_u32_e32 v14, vcc, 0x18bc0000, v12
	s_nop 1
	v_addc_co_u32_e32 v15, vcc, 0, v13, vcc
	global_load_dwordx2 v[68:69], v[14:15], off offset:256
	v_add_co_u32_e32 v14, vcc, 0x18cc0000, v12
	s_nop 1
	v_addc_co_u32_e32 v15, vcc, 0, v13, vcc
	global_load_dwordx2 v[70:71], v[14:15], off offset:256
	v_add_co_u32_e32 v14, vcc, 0x18dc0000, v12
	s_nop 1
	v_addc_co_u32_e32 v15, vcc, 0, v13, vcc
	global_load_dwordx2 v[72:73], v[14:15], off offset:256
	v_add_co_u32_e32 v14, vcc, 0x18ec0000, v12
	s_nop 1
	v_addc_co_u32_e32 v15, vcc, 0, v13, vcc
	global_load_dwordx2 v[74:75], v[14:15], off offset:256
	v_add_co_u32_e32 v14, vcc, 0x18fc0000, v12
	s_nop 1
	v_addc_co_u32_e32 v15, vcc, 0, v13, vcc
	global_load_dwordx2 v[76:77], v[14:15], off offset:256
	v_add_co_u32_e32 v14, vcc, 0x190c0000, v12
	s_nop 1
	v_addc_co_u32_e32 v15, vcc, 0, v13, vcc
	global_load_dwordx2 v[78:79], v[14:15], off offset:256
	v_add_co_u32_e32 v14, vcc, 0x191c0000, v12
	s_nop 1
	v_addc_co_u32_e32 v15, vcc, 0, v13, vcc
	global_load_dwordx2 v[80:81], v[14:15], off offset:256
	v_add_co_u32_e32 v14, vcc, 0x192c0000, v12
	s_nop 1
	v_addc_co_u32_e32 v15, vcc, 0, v13, vcc
	global_load_dwordx2 v[82:83], v[14:15], off offset:256
	v_add_co_u32_e32 v14, vcc, 0x193c0000, v12
	s_nop 1
	v_addc_co_u32_e32 v15, vcc, 0, v13, vcc
	global_load_dwordx2 v[84:85], v[14:15], off offset:256
	v_add_co_u32_e32 v14, vcc, 0x194c0000, v12
	s_nop 1
	v_addc_co_u32_e32 v15, vcc, 0, v13, vcc
	global_load_dwordx2 v[86:87], v[14:15], off offset:256
	v_add_co_u32_e32 v14, vcc, 0x195c0000, v12
	s_nop 1
	v_addc_co_u32_e32 v15, vcc, 0, v13, vcc
	global_load_dwordx2 v[88:89], v[14:15], off offset:256
	v_add_co_u32_e32 v14, vcc, 0x196c0000, v12
	s_nop 1
	v_addc_co_u32_e32 v15, vcc, 0, v13, vcc
	global_load_dwordx2 v[90:91], v[14:15], off offset:256
	v_add_co_u32_e32 v14, vcc, 0x197c0000, v12
	s_nop 1
	v_addc_co_u32_e32 v15, vcc, 0, v13, vcc
	global_load_dwordx2 v[92:93], v[14:15], off offset:256
	v_add_co_u32_e32 v14, vcc, 0x198c0000, v12
	s_nop 1
	v_addc_co_u32_e32 v15, vcc, 0, v13, vcc
	global_load_dwordx2 v[94:95], v[14:15], off offset:256
	v_add_co_u32_e32 v14, vcc, 0x199c0000, v12
	s_nop 1
	v_addc_co_u32_e32 v15, vcc, 0, v13, vcc
	global_load_dwordx2 v[96:97], v[14:15], off offset:256
	v_add_co_u32_e32 v14, vcc, 0x19ac0000, v12
	s_nop 1
	v_addc_co_u32_e32 v15, vcc, 0, v13, vcc
	global_load_dwordx2 v[98:99], v[14:15], off offset:256
	v_add_co_u32_e32 v14, vcc, 0x19bc0000, v12
	s_nop 1
	v_addc_co_u32_e32 v15, vcc, 0, v13, vcc
	global_load_dwordx2 v[100:101], v[14:15], off offset:256
	v_add_co_u32_e32 v14, vcc, 0x19cc0000, v12
	s_nop 1
	v_addc_co_u32_e32 v15, vcc, 0, v13, vcc
	global_load_dwordx2 v[102:103], v[14:15], off offset:256
	s_movk_i32 s0, 0x80
	v_cmp_gt_u32_e32 vcc, s0, v144
	s_and_saveexec_b64 s[0:1], vcc
	s_cbranch_execz .LBB0_677
	s_waitcnt vmcnt(0)
	v_lshlrev_b32_e32 v0, 10, v144
	v_and_b32_e32 v0, 0x18000, v0
	v_mov_b32_e32 v1, 0
	v_and_b32_e32 v6, 31, v144
	v_lshl_add_u64 v[2:3], s[84:85], 0, v[0:1]
	s_mov_b64 s[2:3], 0x17da0100
	v_mov_b64_e32 v[4:5], 0
	v_lshl_add_u64 v[2:3], v[2:3], 0, s[2:3]
	v_cmp_ne_u32_e32 vcc, 0, v6
	v_mov_b32_e32 v5, 0
	s_and_saveexec_b64 s[2:3], vcc
	s_cbranch_execz .LBB0_676
	v_mov_b32_e32 v5, 0
	v_lshlrev_b32_e32 v4, 10, v6
	v_lshl_add_u64 v[4:5], v[2:3], 0, v[4:5]
	global_load_dword v5, v[4:5], off offset:-4
	v_lshlrev_b32_e32 v4, 8, v6

; __device__ __forceinline__ unsigned cvt_pk_bf16(float lo, float hi) { unsigned r; asm volatile("v_cvt_pk_bf16_f32 %0, %1, %2" : "=v"(r) : "v"(lo), "v"(hi)); return r; }
; __device__ __forceinline__ void mlstm_state_scan(const Frame& F) {
;     ...
;     for (int e2 = gt; e2 < 131072; e2 += GT) { const int h = e2 >> 15;
;         f32x2 C = (f32x2){0.f, 0.f};
; #pragma unroll 1
;         for (int c0 = 0; c0 < NCH; c0 += 8) { f32x2 u[8];
; #pragma unroll
;             for (int k = 0; k < 8; ++k) u[k] = *(const f32x2*)(U + (size_t)(c0 + k) * 262144 + (size_t)e2 * 2);
; #pragma unroll
;             for (int k = 0; k < 8; ++k) { *(unsigned*)(CST + (size_t)(c0 + k) * 262144 + (size_t)e2 * 2) = cvt_pk_bf16(C[0], C[1]); C = C * sdec[h * 32 + c0 + k] + u[k]; } }
;         *(f32x2*)(F.out + O_CP + (size_t)e2 * 2) = C; }
.LBB0_679:
	v_ashrrev_i32_e32 v5, 10, v4
	v_lshlrev_b32_e32 v5, 2, v5
	v_and_b32_e32 v5, 0xffffff80, v5
	v_add_u32_e32 v5, 0, v5
	ds_read_b128 v[108:111], v5
	ds_read_b128 v[112:115], v5 offset:16
	ds_read_b128 v[116:119], v5 offset:32
	ds_read_b128 v[120:123], v5 offset:48
	ds_read_b128 v[124:127], v5 offset:64
	ds_read_b128 v[128:131], v5 offset:80
	ds_read_b128 v[132:135], v5 offset:96
	ds_read_b128 v[136:139], v5 offset:112
	v_mov_b32_e32 v10, 0
	v_mov_b32_e32 v11, v10
	v_lshl_add_u64 v[6:7], s[84:85], 0, v[2:3]
	s_waitcnt lgkmcnt(0)
	v_cvt_pk_bf16_f32 v35, v10, v11
	v_add_co_u32_e32 v32, vcc, 0x19de0000, v6
	s_waitcnt vmcnt(31)
	v_pk_fma_f32 v[10:11], v[10:11], v[108:109], v[40:41] op_sel_hi:[1,0,1]
	v_addc_co_u32_e32 v33, vcc, 0, v7, vcc
	global_store_dword v[32:33], v35, off offset:256
	v_cvt_pk_bf16_f32 v35, v10, v11
	v_add_co_u32_e32 v32, vcc, 0x19e60000, v6
	s_waitcnt vmcnt(31)
	v_pk_fma_f32 v[10:11], v[10:11], v[108:109], v[42:43] op_sel:[0,1,0] op_sel_hi:[1,1,1]
	v_addc_co_u32_e32 v33, vcc, 0, v7, vcc
	global_store_dword v[32:33], v35, off offset:256
	v_cvt_pk_bf16_f32 v35, v10, v11
	v_add_co_u32_e32 v32, vcc, 0x19ee0000, v6
	s_waitcnt vmcnt(31)
	v_pk_fma_f32 v[10:11], v[10:11], v[110:111], v[44:45] op_sel_hi:[1,0,1]
	v_addc_co_u32_e32 v33, vcc, 0, v7, vcc
	global_store_dword v[32:33], v35, off offset:256
	v_cvt_pk_bf16_f32 v35, v10, v11
	v_add_co_u32_e32 v32, vcc, 0x19f60000, v6
	s_waitcnt vmcnt(31)
	v_pk_fma_f32 v[10:11], v[10:11], v[110:111], v[46:47] op_sel:[0,1,0] op_sel_hi:[1,1,1]
	v_addc_co_u32_e32 v33, vcc, 0, v7, vcc
	global_store_dword v[32:33], v35, off offset:256
	v_cvt_pk_bf16_f32 v35, v10, v11
	v_add_co_u32_e32 v32, vcc, 0x19fe0000, v6
	s_waitcnt vmcnt(31)
	v_pk_fma_f32 v[10:11], v[10:11], v[112:113], v[48:49] op_sel_hi:[1,0,1]
	v_addc_co_u32_e32 v33, vcc, 0, v7, vcc
	global_store_dword v[32:33], v35, off offset:256
	v_cvt_pk_bf16_f32 v35, v10, v11
	v_add_co_u32_e32 v32, vcc, 0x1a060000, v6
	s_waitcnt vmcnt(31)
	v_pk_fma_f32 v[10:11], v[10:11], v[112:113], v[50:51] op_sel:[0,1,0] op_sel_hi:[1,1,1]
	v_addc_co_u32_e32 v33, vcc, 0, v7, vcc
	global_store_dword v[32:33], v35, off offset:256
	v_cvt_pk_bf16_f32 v35, v10, v11
	v_add_co_u32_e32 v32, vcc, 0x1a0e0000, v6
	s_waitcnt vmcnt(31)
	v_pk_fma_f32 v[10:11], v[10:11], v[114:115], v[52:53] op_sel_hi:[1,0,1]
	v_addc_co_u32_e32 v33, vcc, 0, v7, vcc
	global_store_dword v[32:33], v35, off offset:256
	v_cvt_pk_bf16_f32 v35, v10, v11
	v_add_co_u32_e32 v32, vcc, 0x1a160000, v6
	s_waitcnt vmcnt(31)
	v_pk_fma_f32 v[10:11], v[10:11], v[114:115], v[54:55] op_sel:[0,1,0] op_sel_hi:[1,1,1]
	v_addc_co_u32_e32 v33, vcc, 0, v7, vcc
	global_store_dword v[32:33], v35, off offset:256
	v_cvt_pk_bf16_f32 v35, v10, v11
	v_add_co_u32_e32 v32, vcc, 0x1a1e0000, v6
	s_waitcnt vmcnt(31)
	v_pk_fma_f32 v[10:11], v[10:11], v[116:117], v[56:57] op_sel_hi:[1,0,1]
	v_addc_co_u32_e32 v33, vcc, 0, v7, vcc
	global_store_dword v[32:33], v35, off offset:256
	v_cvt_pk_bf16_f32 v35, v10, v11
	v_add_co_u32_e32 v32, vcc, 0x1a260000, v6
	s_waitcnt vmcnt(31)
	v_pk_fma_f32 v[10:11], v[10:11], v[116:117], v[58:59] op_sel:[0,1,0] op_sel_hi:[1,1,1]
	v_addc_co_u32_e32 v33, vcc, 0, v7, vcc
	global_store_dword v[32:33], v35, off offset:256
	v_cvt_pk_bf16_f32 v35, v10, v11
	v_add_co_u32_e32 v32, vcc, 0x1a2e0000, v6
	s_waitcnt vmcnt(31)
	v_pk_fma_f32 v[10:11], v[10:11], v[118:119], v[60:61] op_sel_hi:[1,0,1]
	v_addc_co_u32_e32 v33, vcc, 0, v7, vcc
	global_store_dword v[32:33], v35, off offset:256
	v_cvt_pk_bf16_f32 v35, v10, v11
	v_add_co_u32_e32 v32, vcc, 0x1a360000, v6
	s_waitcnt vmcnt(31)
	v_pk_fma_f32 v[10:11], v[10:11], v[118:119], v[62:63] op_sel:[0,1,0] op_sel_hi:[1,1,1]
	v_addc_co_u32_e32 v33, vcc, 0, v7, vcc
	global_store_dword v[32:33], v35, off offset:256
	v_cvt_pk_bf16_f32 v35, v10, v11
	v_add_co_u32_e32 v32, vcc, 0x1a3e0000, v6
	s_waitcnt vmcnt(31)
	v_pk_fma_f32 v[10:11], v[10:11], v[120:121], v[64:65] op_sel_hi:[1,0,1]
	v_addc_co_u32_e32 v33, vcc, 0, v7, vcc
	global_store_dword v[32:33], v35, off offset:256
	v_cvt_pk_bf16_f32 v35, v10, v11
	v_add_co_u32_e32 v32, vcc, 0x1a460000, v6
	s_waitcnt vmcnt(31)
	v_pk_fma_f32 v[10:11], v[10:11], v[120:121], v[66:67] op_sel:[0,1,0] op_sel_hi:[1,1,1]
	v_addc_co_u32_e32 v33, vcc, 0, v7, vcc
	global_store_dword v[32:33], v35, off offset:256
	v_cvt_pk_bf16_f32 v35, v10, v11
	v_add_co_u32_e32 v32, vcc, 0x1a4e0000, v6
	s_waitcnt vmcnt(31)
	v_pk_fma_f32 v[10:11], v[10:11], v[122:123], v[68:69] op_sel_hi:[1,0,1]
	v_addc_co_u32_e32 v33, vcc, 0, v7, vcc
	global_store_dword v[32:33], v35, off offset:256
	v_cvt_pk_bf16_f32 v35, v10, v11
	v_add_co_u32_e32 v32, vcc, 0x1a560000, v6
	s_waitcnt vmcnt(31)
; __device__ __forceinline__ unsigned cvt_pk_bf16(float lo, float hi) { unsigned r; asm volatile("v_cvt_pk_bf16_f32 %0, %1, %2" : "=v"(r) : "v"(lo), "v"(hi)); return r; }
; __device__ __forceinline__ void mlstm_state_scan(const Frame& F) {
;     ...
;     for (int e2 = gt; e2 < 131072; e2 += GT) { const int h = e2 >> 15;
;         f32x2 C = (f32x2){0.f, 0.f};
; #pragma unroll 1
;         for (int c0 = 0; c0 < NCH; c0 += 8) { f32x2 u[8];
; #pragma unroll
;             for (int k = 0; k < 8; ++k) u[k] = *(const f32x2*)(U + (size_t)(c0 + k) * 262144 + (size_t)e2 * 2);
; #pragma unroll
;             for (int k = 0; k < 8; ++k) { *(unsigned*)(CST + (size_t)(c0 + k) * 262144 + (size_t)e2 * 2) = cvt_pk_bf16(C[0], C[1]); C = C * sdec[h * 32 + c0 + k] + u[k]; } }
;         *(f32x2*)(F.out + O_CP + (size_t)e2 * 2) = C; }
	v_pk_fma_f32 v[10:11], v[10:11], v[122:123], v[70:71] op_sel:[0,1,0] op_sel_hi:[1,1,1]
	v_addc_co_u32_e32 v33, vcc, 0, v7, vcc
	global_store_dword v[32:33], v35, off offset:256
	v_cvt_pk_bf16_f32 v35, v10, v11
	v_add_co_u32_e32 v32, vcc, 0x1a5e0000, v6
	s_waitcnt vmcnt(31)
	v_pk_fma_f32 v[10:11], v[10:11], v[124:125], v[72:73] op_sel_hi:[1,0,1]
	v_addc_co_u32_e32 v33, vcc, 0, v7, vcc
	global_store_dword v[32:33], v35, off offset:256
	v_cvt_pk_bf16_f32 v35, v10, v11
	v_add_co_u32_e32 v32, vcc, 0x1a660000, v6
	s_waitcnt vmcnt(31)
	v_pk_fma_f32 v[10:11], v[10:11], v[124:125], v[74:75] op_sel:[0,1,0] op_sel_hi:[1,1,1]
	v_addc_co_u32_e32 v33, vcc, 0, v7, vcc
	global_store_dword v[32:33], v35, off offset:256
	v_cvt_pk_bf16_f32 v35, v10, v11
	v_add_co_u32_e32 v32, vcc, 0x1a6e0000, v6
	s_waitcnt vmcnt(31)
	v_pk_fma_f32 v[10:11], v[10:11], v[126:127], v[76:77] op_sel_hi:[1,0,1]
	v_addc_co_u32_e32 v33, vcc, 0, v7, vcc
	global_store_dword v[32:33], v35, off offset:256
	v_cvt_pk_bf16_f32 v35, v10, v11
	v_add_co_u32_e32 v32, vcc, 0x1a760000, v6
	s_waitcnt vmcnt(31)
	v_pk_fma_f32 v[10:11], v[10:11], v[126:127], v[78:79] op_sel:[0,1,0] op_sel_hi:[1,1,1]
	v_addc_co_u32_e32 v33, vcc, 0, v7, vcc
	global_store_dword v[32:33], v35, off offset:256
	v_cvt_pk_bf16_f32 v35, v10, v11
	v_add_co_u32_e32 v32, vcc, 0x1a7e0000, v6
	s_waitcnt vmcnt(31)
	v_pk_fma_f32 v[10:11], v[10:11], v[128:129], v[80:81] op_sel_hi:[1,0,1]
	v_addc_co_u32_e32 v33, vcc, 0, v7, vcc
	global_store_dword v[32:33], v35, off offset:256
	v_cvt_pk_bf16_f32 v35, v10, v11
	v_add_co_u32_e32 v32, vcc, 0x1a860000, v6
	s_waitcnt vmcnt(31)
	v_pk_fma_f32 v[10:11], v[10:11], v[128:129], v[82:83] op_sel:[0,1,0] op_sel_hi:[1,1,1]
	v_addc_co_u32_e32 v33, vcc, 0, v7, vcc
	global_store_dword v[32:33], v35, off offset:256
	v_cvt_pk_bf16_f32 v35, v10, v11
	v_add_co_u32_e32 v32, vcc, 0x1a8e0000, v6
	s_waitcnt vmcnt(31)
	v_pk_fma_f32 v[10:11], v[10:11], v[130:131], v[84:85] op_sel_hi:[1,0,1]
	v_addc_co_u32_e32 v33, vcc, 0, v7, vcc
	global_store_dword v[32:33], v35, off offset:256
	v_cvt_pk_bf16_f32 v35, v10, v11
	v_add_co_u32_e32 v32, vcc, 0x1a960000, v6
	s_waitcnt vmcnt(31)
	v_pk_fma_f32 v[10:11], v[10:11], v[130:131], v[86:87] op_sel:[0,1,0] op_sel_hi:[1,1,1]
	v_addc_co_u32_e32 v33, vcc, 0, v7, vcc
	global_store_dword v[32:33], v35, off offset:256
	v_cvt_pk_bf16_f32 v35, v10, v11
	v_add_co_u32_e32 v32, vcc, 0x1a9e0000, v6
	s_waitcnt vmcnt(31)
	v_pk_fma_f32 v[10:11], v[10:11], v[132:133], v[88:89] op_sel_hi:[1,0,1]
	v_addc_co_u32_e32 v33, vcc, 0, v7, vcc
	global_store_dword v[32:33], v35, off offset:256
	v_cvt_pk_bf16_f32 v35, v10, v11
	v_add_co_u32_e32 v32, vcc, 0x1aa60000, v6
	s_waitcnt vmcnt(31)
	v_pk_fma_f32 v[10:11], v[10:11], v[132:133], v[90:91] op_sel:[0,1,0] op_sel_hi:[1,1,1]
	v_addc_co_u32_e32 v33, vcc, 0, v7, vcc
	global_store_dword v[32:33], v35, off offset:256
	v_cvt_pk_bf16_f32 v35, v10, v11
	v_add_co_u32_e32 v32, vcc, 0x1aae0000, v6
	s_waitcnt vmcnt(31)
	v_pk_fma_f32 v[10:11], v[10:11], v[134:135], v[92:93] op_sel_hi:[1,0,1]
	v_addc_co_u32_e32 v33, vcc, 0, v7, vcc
	global_store_dword v[32:33], v35, off offset:256
	v_cvt_pk_bf16_f32 v35, v10, v11
	v_add_co_u32_e32 v32, vcc, 0x1ab60000, v6
	s_waitcnt vmcnt(31)
	v_pk_fma_f32 v[10:11], v[10:11], v[134:135], v[94:95] op_sel:[0,1,0] op_sel_hi:[1,1,1]
	v_addc_co_u32_e32 v33, vcc, 0, v7, vcc
	global_store_dword v[32:33], v35, off offset:256
	v_cvt_pk_bf16_f32 v35, v10, v11
	v_add_co_u32_e32 v32, vcc, 0x1abe0000, v6
	s_waitcnt vmcnt(31)
	v_pk_fma_f32 v[10:11], v[10:11], v[136:137], v[96:97] op_sel_hi:[1,0,1]
	v_addc_co_u32_e32 v33, vcc, 0, v7, vcc
	global_store_dword v[32:33], v35, off offset:256
	v_cvt_pk_bf16_f32 v35, v10, v11
	v_add_co_u32_e32 v32, vcc, 0x1ac60000, v6
	s_waitcnt vmcnt(31)
	v_pk_fma_f32 v[10:11], v[10:11], v[136:137], v[98:99] op_sel:[0,1,0] op_sel_hi:[1,1,1]
	v_addc_co_u32_e32 v33, vcc, 0, v7, vcc
	global_store_dword v[32:33], v35, off offset:256
	v_cvt_pk_bf16_f32 v35, v10, v11
	v_add_co_u32_e32 v32, vcc, 0x1ace0000, v6
	s_waitcnt vmcnt(31)
	v_pk_fma_f32 v[10:11], v[10:11], v[138:139], v[100:101] op_sel_hi:[1,0,1]
	v_addc_co_u32_e32 v33, vcc, 0, v7, vcc
	global_store_dword v[32:33], v35, off offset:256
	v_cvt_pk_bf16_f32 v35, v10, v11
	v_add_co_u32_e32 v32, vcc, 0x1ad60000, v6
	s_waitcnt vmcnt(31)
	v_pk_fma_f32 v[10:11], v[10:11], v[138:139], v[102:103] op_sel:[0,1,0] op_sel_hi:[1,1,1]
	v_addc_co_u32_e32 v33, vcc, 0, v7, vcc
	global_store_dword v[32:33], v35, off offset:256
	v_ashrrev_i32_e32 v5, 31, v4
	v_lshl_add_u64 v[6:7], v[4:5], 3, s[2:3]
	v_add_u32_e32 v4, s20, v4
	v_cmp_lt_i32_e32 vcc, s14, v4
	v_lshl_add_u64 v[0:1], v[0:1], 0, s[4:5]
	s_or_b64 s[8:9], vcc, s[8:9]
	v_lshl_add_u64 v[2:3], v[2:3], 0, s[6:7]
	global_store_dwordx2 v[6:7], v[10:11], off
	s_andn2_b64 exec, exec, s[8:9]
	s_cbranch_execnz .LBB0_679
